# skip useless next-unit tile DMAs in last K-iteration of last unit of GEMM1/GEMM3/FF1 (out-of-line stubs)
# speedup vs baseline: 1.0043x; 1.0007x over previous
.LBB0_228:
	ds_read_b128 v[128:131], v179
	ds_read_b128 v[132:135], v179 offset:1024
	ds_read_b128 v[136:139], v179 offset:2048
	ds_read_b128 v[140:143], v179 offset:3072
	ds_read_b128 v[162:165], v180
	ds_read_b128 v[166:169], v180 offset:1024
	ds_read_b128 v[170:173], v180 offset:2048
	ds_read_b128 v[186:189], v180 offset:3072
	s_add_u32 s8, s6, 0x10000
	s_addc_u32 s9, s7, 0
	s_cmp_eq_u32 s92, 12
	s_cselect_b32 s80, s69, s8
	s_cselect_b32 s81, s18, s9
	s_cselect_b32 s12, s77, vcc_lo
	s_cselect_b32 s13, s71, vcc_hi
	s_add_u32 s10, s80, 0x8000
	s_addc_u32 s11, s81, 0
	s_add_i32 m0, s79, 0xc000
	ds_read_b128 v[190:193], v181
	ds_read_b128 v[194:197], v181 offset:1024
	ds_read_b128 v[198:201], v181 offset:2048
	ds_read_b128 v[202:205], v181 offset:3072
	ds_read_b128 v[206:209], v181 offset:4096
	ds_read_b128 v[210:213], v181 offset:5120
	ds_read_b128 v[214:217], v181 offset:6144
	ds_read_b128 v[218:221], v181 offset:7168
	global_load_lds_dwordx4 v154, s[6:7]
	s_add_i32 m0, s79, 0xe000
	s_nop 0
	global_load_lds_dwordx4 v156, s[6:7]
	s_waitcnt vmcnt(8)
	s_waitcnt lgkmcnt(0)
	s_setprio 1
	s_barrier
	v_mfma_f32_16x16x32_bf16 v[124:127], v[128:131], v[190:193], v[124:127]
	v_mfma_f32_16x16x32_bf16 v[120:123], v[136:139], v[190:193], v[120:123]
	v_mfma_f32_16x16x32_bf16 v[108:111], v[128:131], v[198:201], v[108:111]
	v_mfma_f32_16x16x32_bf16 v[104:107], v[136:139], v[198:201], v[104:107]
	v_mfma_f32_16x16x32_bf16 v[92:95], v[128:131], v[206:209], v[92:95]
	v_mfma_f32_16x16x32_bf16 v[88:91], v[136:139], v[206:209], v[88:91]
	v_mfma_f32_16x16x32_bf16 v[76:79], v[128:131], v[214:217], v[76:79]
	v_mfma_f32_16x16x32_bf16 v[72:75], v[136:139], v[214:217], v[72:75]
	v_mfma_f32_16x16x32_bf16 v[124:127], v[132:135], v[194:197], v[124:127]
	v_mfma_f32_16x16x32_bf16 v[120:123], v[140:143], v[194:197], v[120:123]
	v_mfma_f32_16x16x32_bf16 v[108:111], v[132:135], v[202:205], v[108:111]
	v_mfma_f32_16x16x32_bf16 v[104:107], v[140:143], v[202:205], v[104:107]
	v_mfma_f32_16x16x32_bf16 v[92:95], v[132:135], v[210:213], v[92:95]
	v_mfma_f32_16x16x32_bf16 v[88:91], v[140:143], v[210:213], v[88:91]
	v_mfma_f32_16x16x32_bf16 v[76:79], v[132:135], v[218:221], v[76:79]
	v_mfma_f32_16x16x32_bf16 v[72:75], v[140:143], v[218:221], v[72:75]
	v_mfma_f32_16x16x32_bf16 v[116:119], v[162:165], v[190:193], v[116:119]
	v_mfma_f32_16x16x32_bf16 v[112:115], v[170:173], v[190:193], v[112:115]
	v_mfma_f32_16x16x32_bf16 v[100:103], v[162:165], v[198:201], v[100:103]
	v_mfma_f32_16x16x32_bf16 v[96:99], v[170:173], v[198:201], v[96:99]
	v_mfma_f32_16x16x32_bf16 v[84:87], v[162:165], v[206:209], v[84:87]
	v_mfma_f32_16x16x32_bf16 v[80:83], v[170:173], v[206:209], v[80:83]
	v_mfma_f32_16x16x32_bf16 v[68:71], v[162:165], v[214:217], v[68:71]
	v_mfma_f32_16x16x32_bf16 v[64:67], v[170:173], v[214:217], v[64:67]
	v_mfma_f32_16x16x32_bf16 v[116:119], v[166:169], v[194:197], v[116:119]
	v_mfma_f32_16x16x32_bf16 v[112:115], v[186:189], v[194:197], v[112:115]
	v_mfma_f32_16x16x32_bf16 v[100:103], v[166:169], v[202:205], v[100:103]
	v_mfma_f32_16x16x32_bf16 v[96:99], v[186:189], v[202:205], v[96:99]
	v_mfma_f32_16x16x32_bf16 v[84:87], v[166:169], v[210:213], v[84:87]
	v_mfma_f32_16x16x32_bf16 v[80:83], v[186:189], v[210:213], v[80:83]
	v_mfma_f32_16x16x32_bf16 v[68:71], v[166:169], v[218:221], v[68:71]
	v_mfma_f32_16x16x32_bf16 v[64:67], v[186:189], v[218:221], v[64:67]
	s_barrier
	s_setprio 0
	s_add_i32 s6, s34, s84
	s_mov_b32 m0, s6
	ds_read_b128 v[190:193], v181 offset:16384
	ds_read_b128 v[194:197], v181 offset:17408
	ds_read_b128 v[198:201], v181 offset:18432
	ds_read_b128 v[202:205], v181 offset:19456
	ds_read_b128 v[206:209], v181 offset:20480
	ds_read_b128 v[210:213], v181 offset:21504
	ds_read_b128 v[214:217], v181 offset:22528
	ds_read_b128 v[218:221], v181 offset:23552
	s_cmp_eq_u32 s92, 12
	s_cbranch_scc1 .Lg1_last1
.Lg1_dma1:
	global_load_lds_dwordx4 v146, s[12:13]
	s_add_i32 m0, s6, 0x2000
	s_add_u32 s6, s12, 0x40000
	s_addc_u32 s7, s13, 0
	s_add_i32 s38, s35, s84
	global_load_lds_dwordx4 v150, s[12:13]
	s_mov_b32 m0, s38
	s_nop 0
	global_load_lds_dwordx4 v146, s[6:7]
	s_add_i32 m0, s38, 0x2000
	s_nop 0
	global_load_lds_dwordx4 v150, s[6:7]
	s_mov_b32 m0, s79
	s_nop 0
	global_load_lds_dwordx4 v144, s[80:81]
	s_mov_b32 m0, s85
	s_nop 0
	global_load_lds_dwordx4 v148, s[80:81]
.Lg1_join1:
	s_waitcnt vmcnt(8)
	s_waitcnt lgkmcnt(0)
	s_setprio 1
	s_barrier
	v_mfma_f32_16x16x32_bf16 v[60:63], v[128:131], v[190:193], v[60:63]
	v_mfma_f32_16x16x32_bf16 v[56:59], v[136:139], v[190:193], v[56:59]
	v_mfma_f32_16x16x32_bf16 v[44:47], v[128:131], v[198:201], v[44:47]
	v_mfma_f32_16x16x32_bf16 v[40:43], v[136:139], v[198:201], v[40:43]
	v_mfma_f32_16x16x32_bf16 v[28:31], v[128:131], v[206:209], v[28:31]
	v_mfma_f32_16x16x32_bf16 v[24:27], v[136:139], v[206:209], v[24:27]
	v_mfma_f32_16x16x32_bf16 v[12:15], v[128:131], v[214:217], v[12:15]
	v_mfma_f32_16x16x32_bf16 v[8:11], v[136:139], v[214:217], v[8:11]
	v_mfma_f32_16x16x32_bf16 v[60:63], v[132:135], v[194:197], v[60:63]
	v_mfma_f32_16x16x32_bf16 v[56:59], v[140:143], v[194:197], v[56:59]
	v_mfma_f32_16x16x32_bf16 v[44:47], v[132:135], v[202:205], v[44:47]
	v_mfma_f32_16x16x32_bf16 v[40:43], v[140:143], v[202:205], v[40:43]
	v_mfma_f32_16x16x32_bf16 v[28:31], v[132:135], v[210:213], v[28:31]
	v_mfma_f32_16x16x32_bf16 v[24:27], v[140:143], v[210:213], v[24:27]
	v_mfma_f32_16x16x32_bf16 v[12:15], v[132:135], v[218:221], v[12:15]
	v_mfma_f32_16x16x32_bf16 v[8:11], v[140:143], v[218:221], v[8:11]
	v_mfma_f32_16x16x32_bf16 v[52:55], v[162:165], v[190:193], v[52:55]
	v_mfma_f32_16x16x32_bf16 v[48:51], v[170:173], v[190:193], v[48:51]
	v_mfma_f32_16x16x32_bf16 v[36:39], v[162:165], v[198:201], v[36:39]
	v_mfma_f32_16x16x32_bf16 v[32:35], v[170:173], v[198:201], v[32:35]
	v_mfma_f32_16x16x32_bf16 v[20:23], v[162:165], v[206:209], v[20:23]
	v_mfma_f32_16x16x32_bf16 v[16:19], v[170:173], v[206:209], v[16:19]
	v_mfma_f32_16x16x32_bf16 v[4:7], v[162:165], v[214:217], v[4:7]
	v_mfma_f32_16x16x32_bf16 v[0:3], v[170:173], v[214:217], v[0:3]
	v_mfma_f32_16x16x32_bf16 v[52:55], v[166:169], v[194:197], v[52:55]
	v_mfma_f32_16x16x32_bf16 v[48:51], v[186:189], v[194:197], v[48:51]
	v_mfma_f32_16x16x32_bf16 v[36:39], v[166:169], v[202:205], v[36:39]
	v_mfma_f32_16x16x32_bf16 v[32:35], v[186:189], v[202:205], v[32:35]
	v_mfma_f32_16x16x32_bf16 v[20:23], v[166:169], v[210:213], v[20:23]
	v_mfma_f32_16x16x32_bf16 v[16:19], v[186:189], v[210:213], v[16:19]
	v_mfma_f32_16x16x32_bf16 v[4:7], v[166:169], v[218:221], v[4:7]
	v_mfma_f32_16x16x32_bf16 v[0:3], v[186:189], v[218:221], v[0:3]
	s_barrier
	s_setprio 0
	s_add_i32 s38, 0, 0x18000
	s_add_i32 s39, 0, 0x1c000
	v_add_u32_e32 v140, s38, v178
	v_add_u32_e32 v152, s39, v178
	ds_read_b128 v[128:131], v140
	ds_read_b128 v[132:135], v140 offset:1024
	ds_read_b128 v[136:139], v140 offset:2048
	ds_read_b128 v[140:143], v140 offset:3072
	ds_read_b128 v[162:165], v152
	ds_read_b128 v[166:169], v152 offset:1024
	ds_read_b128 v[170:173], v152 offset:2048
	ds_read_b128 v[186:189], v152 offset:3072
	s_add_u32 s6, s80, 0x4000
	s_addc_u32 s7, s81, 0
	s_mov_b32 m0, s86
	ds_read_b128 v[190:193], v181 offset:32768
	ds_read_b128 v[194:197], v181 offset:33792
	ds_read_b128 v[198:201], v181 offset:34816
	ds_read_b128 v[202:205], v181 offset:35840
	ds_read_b128 v[206:209], v181 offset:36864
	ds_read_b128 v[210:213], v181 offset:37888
	ds_read_b128 v[214:217], v181 offset:38912
	ds_read_b128 v[218:221], v181 offset:39936
	s_cmp_eq_u32 s92, 12
	s_cbranch_scc1 .Lg1_last2
.Lg1_dma2:
	global_load_lds_dwordx4 v144, s[6:7]
	s_mov_b32 m0, s87
	s_nop 0
	global_load_lds_dwordx4 v148, s[6:7]
.Lg1_join2:
	s_waitcnt vmcnt(8)
	s_waitcnt lgkmcnt(0)
	s_setprio 1
	s_barrier
	v_mfma_f32_16x16x32_bf16 v[124:127], v[128:131], v[190:193], v[124:127]
	v_mfma_f32_16x16x32_bf16 v[120:123], v[136:139], v[190:193], v[120:123]
	v_mfma_f32_16x16x32_bf16 v[108:111], v[128:131], v[198:201], v[108:111]
	v_mfma_f32_16x16x32_bf16 v[104:107], v[136:139], v[198:201], v[104:107]
	v_mfma_f32_16x16x32_bf16 v[92:95], v[128:131], v[206:209], v[92:95]
	v_mfma_f32_16x16x32_bf16 v[88:91], v[136:139], v[206:209], v[88:91]
	v_mfma_f32_16x16x32_bf16 v[76:79], v[128:131], v[214:217], v[76:79]
	v_mfma_f32_16x16x32_bf16 v[72:75], v[136:139], v[214:217], v[72:75]
	v_mfma_f32_16x16x32_bf16 v[124:127], v[132:135], v[194:197], v[124:127]
	v_mfma_f32_16x16x32_bf16 v[120:123], v[140:143], v[194:197], v[120:123]
	v_mfma_f32_16x16x32_bf16 v[108:111], v[132:135], v[202:205], v[108:111]
	v_mfma_f32_16x16x32_bf16 v[104:107], v[140:143], v[202:205], v[104:107]
	v_mfma_f32_16x16x32_bf16 v[92:95], v[132:135], v[210:213], v[92:95]
	v_mfma_f32_16x16x32_bf16 v[88:91], v[140:143], v[210:213], v[88:91]
	v_mfma_f32_16x16x32_bf16 v[76:79], v[132:135], v[218:221], v[76:79]
	v_mfma_f32_16x16x32_bf16 v[72:75], v[140:143], v[218:221], v[72:75]
	v_mfma_f32_16x16x32_bf16 v[116:119], v[162:165], v[190:193], v[116:119]
	v_mfma_f32_16x16x32_bf16 v[112:115], v[170:173], v[190:193], v[112:115]
	v_mfma_f32_16x16x32_bf16 v[100:103], v[162:165], v[198:201], v[100:103]
	v_mfma_f32_16x16x32_bf16 v[96:99], v[170:173], v[198:201], v[96:99]
	v_mfma_f32_16x16x32_bf16 v[84:87], v[162:165], v[206:209], v[84:87]
	v_mfma_f32_16x16x32_bf16 v[80:83], v[170:173], v[206:209], v[80:83]
	v_mfma_f32_16x16x32_bf16 v[68:71], v[162:165], v[214:217], v[68:71]
	v_mfma_f32_16x16x32_bf16 v[64:67], v[170:173], v[214:217], v[64:67]
	v_mfma_f32_16x16x32_bf16 v[116:119], v[166:169], v[194:197], v[116:119]
	v_mfma_f32_16x16x32_bf16 v[112:115], v[186:189], v[194:197], v[112:115]
	v_mfma_f32_16x16x32_bf16 v[100:103], v[166:169], v[202:205], v[100:103]
	v_mfma_f32_16x16x32_bf16 v[96:99], v[186:189], v[202:205], v[96:99]
	v_mfma_f32_16x16x32_bf16 v[84:87], v[166:169], v[210:213], v[84:87]
	v_mfma_f32_16x16x32_bf16 v[80:83], v[186:189], v[210:213], v[80:83]
	v_mfma_f32_16x16x32_bf16 v[68:71], v[166:169], v[218:221], v[68:71]
	v_mfma_f32_16x16x32_bf16 v[64:67], v[186:189], v[218:221], v[64:67]
	s_barrier
	s_setprio 0
	s_add_u32 s98, s12, s48
	s_addc_u32 s99, s13, s49
	s_add_i32 s6, s38, s84
	s_mov_b32 m0, s6
	ds_read_b128 v[190:193], v181 offset:49152
	ds_read_b128 v[194:197], v181 offset:50176
	ds_read_b128 v[198:201], v181 offset:51200
	ds_read_b128 v[202:205], v181 offset:52224
	ds_read_b128 v[206:209], v181 offset:53248
	ds_read_b128 v[210:213], v181 offset:54272
	ds_read_b128 v[214:217], v181 offset:55296
	ds_read_b128 v[218:221], v181 offset:56320
	s_cmp_eq_u32 s92, 12
	s_cbranch_scc1 .Lg1_last3
.Lg1_dma3:
	global_load_lds_dwordx4 v146, s[98:99]
	s_add_i32 m0, s6, 0x2000
	s_add_u32 s6, s12, 0x40080
	s_addc_u32 s7, s13, 0
	s_add_i32 s12, s39, s84
	global_load_lds_dwordx4 v150, s[98:99]
	s_mov_b32 m0, s12
	s_nop 0
	global_load_lds_dwordx4 v146, s[6:7]
	s_add_i32 m0, s12, 0x2000
	s_nop 0
	global_load_lds_dwordx4 v150, s[6:7]
	s_mov_b32 m0, s33
	s_nop 0
	global_load_lds_dwordx4 v144, s[10:11]
	s_mov_b32 m0, s56
	s_nop 0
	global_load_lds_dwordx4 v148, s[10:11]
.Lg1_join3:
	s_waitcnt vmcnt(8)
	s_waitcnt lgkmcnt(0)
	s_setprio 1
	s_barrier
	v_mfma_f32_16x16x32_bf16 v[60:63], v[128:131], v[190:193], v[60:63]
	v_mfma_f32_16x16x32_bf16 v[56:59], v[136:139], v[190:193], v[56:59]
	v_mfma_f32_16x16x32_bf16 v[44:47], v[128:131], v[198:201], v[44:47]
	v_mfma_f32_16x16x32_bf16 v[40:43], v[136:139], v[198:201], v[40:43]
	v_mfma_f32_16x16x32_bf16 v[28:31], v[128:131], v[206:209], v[28:31]
	v_mfma_f32_16x16x32_bf16 v[24:27], v[136:139], v[206:209], v[24:27]
	v_mfma_f32_16x16x32_bf16 v[12:15], v[128:131], v[214:217], v[12:15]
	v_mfma_f32_16x16x32_bf16 v[8:11], v[136:139], v[214:217], v[8:11]
	v_mfma_f32_16x16x32_bf16 v[60:63], v[132:135], v[194:197], v[60:63]
	v_mfma_f32_16x16x32_bf16 v[56:59], v[140:143], v[194:197], v[56:59]
	v_mfma_f32_16x16x32_bf16 v[44:47], v[132:135], v[202:205], v[44:47]
	v_mfma_f32_16x16x32_bf16 v[40:43], v[140:143], v[202:205], v[40:43]
	v_mfma_f32_16x16x32_bf16 v[28:31], v[132:135], v[210:213], v[28:31]
	v_mfma_f32_16x16x32_bf16 v[24:27], v[140:143], v[210:213], v[24:27]
	v_mfma_f32_16x16x32_bf16 v[12:15], v[132:135], v[218:221], v[12:15]
	v_mfma_f32_16x16x32_bf16 v[8:11], v[140:143], v[218:221], v[8:11]
	v_mfma_f32_16x16x32_bf16 v[52:55], v[162:165], v[190:193], v[52:55]
	v_mfma_f32_16x16x32_bf16 v[48:51], v[170:173], v[190:193], v[48:51]
	v_mfma_f32_16x16x32_bf16 v[36:39], v[162:165], v[198:201], v[36:39]
	v_mfma_f32_16x16x32_bf16 v[32:35], v[170:173], v[198:201], v[32:35]
	v_mfma_f32_16x16x32_bf16 v[20:23], v[162:165], v[206:209], v[20:23]
	v_mfma_f32_16x16x32_bf16 v[16:19], v[170:173], v[206:209], v[16:19]
	v_mfma_f32_16x16x32_bf16 v[4:7], v[162:165], v[214:217], v[4:7]
	v_mfma_f32_16x16x32_bf16 v[0:3], v[170:173], v[214:217], v[0:3]
	v_mfma_f32_16x16x32_bf16 v[52:55], v[166:169], v[194:197], v[52:55]
	v_mfma_f32_16x16x32_bf16 v[48:51], v[186:189], v[194:197], v[48:51]
	v_mfma_f32_16x16x32_bf16 v[36:39], v[166:169], v[202:205], v[36:39]
	v_mfma_f32_16x16x32_bf16 v[32:35], v[186:189], v[202:205], v[32:35]
	v_mfma_f32_16x16x32_bf16 v[20:23], v[166:169], v[210:213], v[20:23]
	v_mfma_f32_16x16x32_bf16 v[16:19], v[186:189], v[210:213], v[16:19]
	v_mfma_f32_16x16x32_bf16 v[4:7], v[166:169], v[218:221], v[4:7]
	v_mfma_f32_16x16x32_bf16 v[0:3], v[186:189], v[218:221], v[0:3]
	s_barrier
	s_setprio 0
	s_add_i32 s92, s92, 2
	s_add_u32 vcc_lo, vcc_lo, 0x100
	s_addc_u32 vcc_hi, vcc_hi, 0
	s_cmp_gt_u32 s92, 13
	s_mov_b64 s[6:7], s[8:9]
	s_cbranch_scc0 .LBB0_228
	s_and_b64 vcc, exec, s[82:83]
	s_cbranch_vccz .LBB0_231
	s_barrier

.Lg1_last1:
	s_cmp_lt_u32 s91, 8
	s_cbranch_scc1 .Lg1_dma1
	s_add_i32 m0, s6, 0x2000
	s_add_u32 s6, s12, 0x40000
	s_addc_u32 s7, s13, 0
	s_add_i32 s38, s35, s84
	s_mov_b32 m0, s38
	s_add_i32 m0, s38, 0x2000
	s_mov_b32 m0, s79
	s_mov_b32 m0, s85
	s_waitcnt vmcnt(2)
	s_branch .Lg1_join1
.Lg1_last2:
	s_cmp_lt_u32 s91, 8
	s_cbranch_scc1 .Lg1_dma2
	s_mov_b32 m0, s87
	s_waitcnt vmcnt(0)
	s_branch .Lg1_join2
.Lg1_last3:
	s_cmp_lt_u32 s91, 8
	s_cbranch_scc1 .Lg1_dma3
	s_add_i32 m0, s6, 0x2000
	s_add_u32 s6, s12, 0x40080
	s_addc_u32 s7, s13, 0
	s_add_i32 s12, s39, s84
	s_mov_b32 m0, s12
	s_add_i32 m0, s12, 0x2000
	s_mov_b32 m0, s33
	s_mov_b32 m0, s56
	s_branch .Lg1_join3

.LBB0_507:
	ds_read_b128 v[128:131], v229
	ds_read_b128 v[132:135], v229 offset:1024
	ds_read_b128 v[136:139], v229 offset:2048
	ds_read_b128 v[140:143], v229 offset:3072
	ds_read_b128 v[144:147], v230
	ds_read_b128 v[148:151], v230 offset:1024
	ds_read_b128 v[152:155], v230 offset:2048
	ds_read_b128 v[156:159], v230 offset:3072
	s_add_u32 s44, s42, 0x10000
	s_addc_u32 s45, s43, 0
	s_cmp_eq_u32 s83, 12
	s_cselect_b32 s50, s21, s44
	s_cselect_b32 s51, s8, s45
	s_cselect_b32 s48, s29, s80
	s_cselect_b32 s49, s27, s81
	s_add_u32 s46, s50, 0x8000
	s_addc_u32 s47, s51, 0
	s_add_i32 m0, s23, 0xc000
	ds_read_b128 v[160:163], v231
	ds_read_b128 v[164:167], v231 offset:1024
	ds_read_b128 v[168:171], v231 offset:2048
	ds_read_b128 v[172:175], v231 offset:3072
	ds_read_b128 v[176:179], v231 offset:4096
	ds_read_b128 v[180:183], v231 offset:5120
	ds_read_b128 v[184:187], v231 offset:6144
	ds_read_b128 v[188:191], v231 offset:7168
	global_load_lds_dwordx4 v200, s[42:43]
	s_add_i32 m0, s23, 0xe000
	s_nop 0
	global_load_lds_dwordx4 v202, s[42:43]
	s_waitcnt vmcnt(8)
	s_waitcnt lgkmcnt(0)
	s_setprio 1
	s_barrier
	v_mfma_f32_16x16x32_bf16 v[124:127], v[128:131], v[160:163], v[124:127]
	v_mfma_f32_16x16x32_bf16 v[120:123], v[136:139], v[160:163], v[120:123]
	v_mfma_f32_16x16x32_bf16 v[108:111], v[128:131], v[168:171], v[108:111]
	v_mfma_f32_16x16x32_bf16 v[104:107], v[136:139], v[168:171], v[104:107]
	v_mfma_f32_16x16x32_bf16 v[92:95], v[128:131], v[176:179], v[92:95]
	v_mfma_f32_16x16x32_bf16 v[88:91], v[136:139], v[176:179], v[88:91]
	v_mfma_f32_16x16x32_bf16 v[76:79], v[128:131], v[184:187], v[76:79]
	v_mfma_f32_16x16x32_bf16 v[72:75], v[136:139], v[184:187], v[72:75]
	v_mfma_f32_16x16x32_bf16 v[124:127], v[132:135], v[164:167], v[124:127]
	v_mfma_f32_16x16x32_bf16 v[120:123], v[140:143], v[164:167], v[120:123]
	v_mfma_f32_16x16x32_bf16 v[108:111], v[132:135], v[172:175], v[108:111]
	v_mfma_f32_16x16x32_bf16 v[104:107], v[140:143], v[172:175], v[104:107]
	v_mfma_f32_16x16x32_bf16 v[92:95], v[132:135], v[180:183], v[92:95]
	v_mfma_f32_16x16x32_bf16 v[88:91], v[140:143], v[180:183], v[88:91]
	v_mfma_f32_16x16x32_bf16 v[76:79], v[132:135], v[188:191], v[76:79]
	v_mfma_f32_16x16x32_bf16 v[72:75], v[140:143], v[188:191], v[72:75]
	v_mfma_f32_16x16x32_bf16 v[116:119], v[144:147], v[160:163], v[116:119]
	v_mfma_f32_16x16x32_bf16 v[112:115], v[152:155], v[160:163], v[112:115]
	v_mfma_f32_16x16x32_bf16 v[100:103], v[144:147], v[168:171], v[100:103]
	v_mfma_f32_16x16x32_bf16 v[96:99], v[152:155], v[168:171], v[96:99]
	v_mfma_f32_16x16x32_bf16 v[84:87], v[144:147], v[176:179], v[84:87]
	v_mfma_f32_16x16x32_bf16 v[80:83], v[152:155], v[176:179], v[80:83]
	v_mfma_f32_16x16x32_bf16 v[68:71], v[144:147], v[184:187], v[68:71]
	v_mfma_f32_16x16x32_bf16 v[64:67], v[152:155], v[184:187], v[64:67]
	v_mfma_f32_16x16x32_bf16 v[116:119], v[148:151], v[164:167], v[116:119]
	v_mfma_f32_16x16x32_bf16 v[112:115], v[156:159], v[164:167], v[112:115]
	v_mfma_f32_16x16x32_bf16 v[100:103], v[148:151], v[172:175], v[100:103]
	v_mfma_f32_16x16x32_bf16 v[96:99], v[156:159], v[172:175], v[96:99]
	v_mfma_f32_16x16x32_bf16 v[84:87], v[148:151], v[180:183], v[84:87]
	v_mfma_f32_16x16x32_bf16 v[80:83], v[156:159], v[180:183], v[80:83]
	v_mfma_f32_16x16x32_bf16 v[68:71], v[148:151], v[188:191], v[68:71]
	v_mfma_f32_16x16x32_bf16 v[64:67], v[156:159], v[188:191], v[64:67]
	s_barrier
	s_setprio 0
	s_add_i32 s42, s77, s35
	s_mov_b32 m0, s42
	ds_read_b128 v[160:163], v231 offset:16384
	ds_read_b128 v[164:167], v231 offset:17408
	ds_read_b128 v[168:171], v231 offset:18432
	ds_read_b128 v[172:175], v231 offset:19456
	ds_read_b128 v[176:179], v231 offset:20480
	ds_read_b128 v[180:183], v231 offset:21504
	ds_read_b128 v[184:187], v231 offset:22528
	ds_read_b128 v[188:191], v231 offset:23552
	s_cmp_eq_u32 s83, 12
	s_cbranch_scc1 .Lg3_last1
.Lg3_dma1:
	global_load_lds_dwordx4 v194, s[48:49]
	s_add_i32 m0, s42, 0x2000
	s_add_u32 s42, s48, 0x40000
	s_addc_u32 s43, s49, 0
	s_add_i32 s84, s78, s35
	global_load_lds_dwordx4 v198, s[48:49]
	s_mov_b32 m0, s84
	s_nop 0
	global_load_lds_dwordx4 v194, s[42:43]
	s_add_i32 m0, s84, 0x2000
	s_nop 0
	global_load_lds_dwordx4 v198, s[42:43]
	s_mov_b32 m0, s23
	s_nop 0
	global_load_lds_dwordx4 v192, s[50:51]
	s_mov_b32 m0, s56
	s_nop 0
	global_load_lds_dwordx4 v196, s[50:51]
.Lg3_join1:
	s_waitcnt vmcnt(8)
	s_waitcnt lgkmcnt(0)
	s_setprio 1
	s_barrier
	v_mfma_f32_16x16x32_bf16 v[60:63], v[128:131], v[160:163], v[60:63]
	v_mfma_f32_16x16x32_bf16 v[56:59], v[136:139], v[160:163], v[56:59]
	v_mfma_f32_16x16x32_bf16 v[44:47], v[128:131], v[168:171], v[44:47]
	v_mfma_f32_16x16x32_bf16 v[40:43], v[136:139], v[168:171], v[40:43]
	v_mfma_f32_16x16x32_bf16 v[28:31], v[128:131], v[176:179], v[28:31]
	v_mfma_f32_16x16x32_bf16 v[24:27], v[136:139], v[176:179], v[24:27]
	v_mfma_f32_16x16x32_bf16 v[12:15], v[128:131], v[184:187], v[12:15]
	v_mfma_f32_16x16x32_bf16 v[8:11], v[136:139], v[184:187], v[8:11]
	v_mfma_f32_16x16x32_bf16 v[60:63], v[132:135], v[164:167], v[60:63]
	v_mfma_f32_16x16x32_bf16 v[56:59], v[140:143], v[164:167], v[56:59]
	v_mfma_f32_16x16x32_bf16 v[44:47], v[132:135], v[172:175], v[44:47]
	v_mfma_f32_16x16x32_bf16 v[40:43], v[140:143], v[172:175], v[40:43]
	v_mfma_f32_16x16x32_bf16 v[28:31], v[132:135], v[180:183], v[28:31]
	v_mfma_f32_16x16x32_bf16 v[24:27], v[140:143], v[180:183], v[24:27]
	v_mfma_f32_16x16x32_bf16 v[12:15], v[132:135], v[188:191], v[12:15]
	v_mfma_f32_16x16x32_bf16 v[8:11], v[140:143], v[188:191], v[8:11]
	v_mfma_f32_16x16x32_bf16 v[52:55], v[144:147], v[160:163], v[52:55]
	v_mfma_f32_16x16x32_bf16 v[48:51], v[152:155], v[160:163], v[48:51]
	v_mfma_f32_16x16x32_bf16 v[36:39], v[144:147], v[168:171], v[36:39]
	v_mfma_f32_16x16x32_bf16 v[32:35], v[152:155], v[168:171], v[32:35]
	v_mfma_f32_16x16x32_bf16 v[20:23], v[144:147], v[176:179], v[20:23]
	v_mfma_f32_16x16x32_bf16 v[16:19], v[152:155], v[176:179], v[16:19]
	v_mfma_f32_16x16x32_bf16 v[4:7], v[144:147], v[184:187], v[4:7]
	v_mfma_f32_16x16x32_bf16 v[0:3], v[152:155], v[184:187], v[0:3]
	v_mfma_f32_16x16x32_bf16 v[52:55], v[148:151], v[164:167], v[52:55]
	v_mfma_f32_16x16x32_bf16 v[48:51], v[156:159], v[164:167], v[48:51]
	v_mfma_f32_16x16x32_bf16 v[36:39], v[148:151], v[172:175], v[36:39]
	v_mfma_f32_16x16x32_bf16 v[32:35], v[156:159], v[172:175], v[32:35]
	v_mfma_f32_16x16x32_bf16 v[20:23], v[148:151], v[180:183], v[20:23]
	v_mfma_f32_16x16x32_bf16 v[16:19], v[156:159], v[180:183], v[16:19]
	v_mfma_f32_16x16x32_bf16 v[4:7], v[148:151], v[188:191], v[4:7]
	v_mfma_f32_16x16x32_bf16 v[0:3], v[156:159], v[188:191], v[0:3]
	s_barrier
	s_setprio 0
	s_add_i32 s84, 0, 0x18000
	s_add_i32 s85, 0, 0x1c000
	v_add_u32_e32 v140, s84, v228
	v_add_u32_e32 v156, s85, v228
	ds_read_b128 v[128:131], v140
	ds_read_b128 v[132:135], v140 offset:1024
	ds_read_b128 v[136:139], v140 offset:2048
	ds_read_b128 v[140:143], v140 offset:3072
	ds_read_b128 v[144:147], v156
	ds_read_b128 v[148:151], v156 offset:1024
	ds_read_b128 v[152:155], v156 offset:2048
	ds_read_b128 v[156:159], v156 offset:3072
	s_add_u32 s42, s50, 0x2000
	s_addc_u32 s43, s51, 0
	s_mov_b32 m0, s57
	ds_read_b128 v[160:163], v231 offset:32768
	ds_read_b128 v[164:167], v231 offset:33792
	ds_read_b128 v[168:171], v231 offset:34816
	ds_read_b128 v[172:175], v231 offset:35840
	ds_read_b128 v[176:179], v231 offset:36864
	ds_read_b128 v[180:183], v231 offset:37888
	ds_read_b128 v[184:187], v231 offset:38912
	ds_read_b128 v[188:191], v231 offset:39936
	s_cmp_eq_u32 s83, 12
	s_cbranch_scc1 .Lg3_last2
.Lg3_dma2:
	global_load_lds_dwordx4 v192, s[42:43]
	s_mov_b32 m0, s59
	s_nop 0
	global_load_lds_dwordx4 v196, s[42:43]
.Lg3_join2:
	s_waitcnt vmcnt(8)
	s_waitcnt lgkmcnt(0)
	s_setprio 1
	s_barrier
	v_mfma_f32_16x16x32_bf16 v[124:127], v[128:131], v[160:163], v[124:127]
	v_mfma_f32_16x16x32_bf16 v[120:123], v[136:139], v[160:163], v[120:123]
	v_mfma_f32_16x16x32_bf16 v[108:111], v[128:131], v[168:171], v[108:111]
	v_mfma_f32_16x16x32_bf16 v[104:107], v[136:139], v[168:171], v[104:107]
	v_mfma_f32_16x16x32_bf16 v[92:95], v[128:131], v[176:179], v[92:95]
	v_mfma_f32_16x16x32_bf16 v[88:91], v[136:139], v[176:179], v[88:91]
	v_mfma_f32_16x16x32_bf16 v[76:79], v[128:131], v[184:187], v[76:79]
	v_mfma_f32_16x16x32_bf16 v[72:75], v[136:139], v[184:187], v[72:75]
	v_mfma_f32_16x16x32_bf16 v[124:127], v[132:135], v[164:167], v[124:127]
	v_mfma_f32_16x16x32_bf16 v[120:123], v[140:143], v[164:167], v[120:123]
	v_mfma_f32_16x16x32_bf16 v[108:111], v[132:135], v[172:175], v[108:111]
	v_mfma_f32_16x16x32_bf16 v[104:107], v[140:143], v[172:175], v[104:107]
	v_mfma_f32_16x16x32_bf16 v[92:95], v[132:135], v[180:183], v[92:95]
	v_mfma_f32_16x16x32_bf16 v[88:91], v[140:143], v[180:183], v[88:91]
	v_mfma_f32_16x16x32_bf16 v[76:79], v[132:135], v[188:191], v[76:79]
	v_mfma_f32_16x16x32_bf16 v[72:75], v[140:143], v[188:191], v[72:75]
	v_mfma_f32_16x16x32_bf16 v[116:119], v[144:147], v[160:163], v[116:119]
	v_mfma_f32_16x16x32_bf16 v[112:115], v[152:155], v[160:163], v[112:115]
	v_mfma_f32_16x16x32_bf16 v[100:103], v[144:147], v[168:171], v[100:103]
	v_mfma_f32_16x16x32_bf16 v[96:99], v[152:155], v[168:171], v[96:99]
	v_mfma_f32_16x16x32_bf16 v[84:87], v[144:147], v[176:179], v[84:87]
	v_mfma_f32_16x16x32_bf16 v[80:83], v[152:155], v[176:179], v[80:83]
	v_mfma_f32_16x16x32_bf16 v[68:71], v[144:147], v[184:187], v[68:71]
	v_mfma_f32_16x16x32_bf16 v[64:67], v[152:155], v[184:187], v[64:67]
	v_mfma_f32_16x16x32_bf16 v[116:119], v[148:151], v[164:167], v[116:119]
	v_mfma_f32_16x16x32_bf16 v[112:115], v[156:159], v[164:167], v[112:115]
	v_mfma_f32_16x16x32_bf16 v[100:103], v[148:151], v[172:175], v[100:103]
	v_mfma_f32_16x16x32_bf16 v[96:99], v[156:159], v[172:175], v[96:99]
	v_mfma_f32_16x16x32_bf16 v[84:87], v[148:151], v[180:183], v[84:87]
	v_mfma_f32_16x16x32_bf16 v[80:83], v[156:159], v[180:183], v[80:83]
	v_mfma_f32_16x16x32_bf16 v[68:71], v[148:151], v[188:191], v[68:71]
	v_mfma_f32_16x16x32_bf16 v[64:67], v[156:159], v[188:191], v[64:67]
	s_barrier
	s_setprio 0
	s_add_u32 s98, s48, s16
	s_addc_u32 s99, s49, s17
	s_add_i32 s42, s84, s35
	s_mov_b32 m0, s42
	ds_read_b128 v[160:163], v231 offset:49152
	ds_read_b128 v[164:167], v231 offset:50176
	ds_read_b128 v[168:171], v231 offset:51200
	ds_read_b128 v[172:175], v231 offset:52224
	ds_read_b128 v[176:179], v231 offset:53248
	ds_read_b128 v[180:183], v231 offset:54272
	ds_read_b128 v[184:187], v231 offset:55296
	ds_read_b128 v[188:191], v231 offset:56320
	s_cmp_eq_u32 s83, 12
	s_cbranch_scc1 .Lg3_last3
.Lg3_dma3:
	global_load_lds_dwordx4 v194, s[98:99]
	s_add_i32 m0, s42, 0x2000
	s_add_u32 s42, s48, 0x40080
	s_addc_u32 s43, s49, 0
	s_add_i32 s48, s85, s35
	global_load_lds_dwordx4 v198, s[98:99]
	s_mov_b32 m0, s48
	s_nop 0
	global_load_lds_dwordx4 v194, s[42:43]
	s_add_i32 m0, s48, 0x2000
	s_nop 0
	global_load_lds_dwordx4 v198, s[42:43]
	s_mov_b32 m0, s75
	s_nop 0
	global_load_lds_dwordx4 v192, s[46:47]
	s_mov_b32 m0, s76
	s_nop 0
	global_load_lds_dwordx4 v196, s[46:47]
.Lg3_join3:
	s_waitcnt vmcnt(8)
	s_waitcnt lgkmcnt(0)
	s_setprio 1
	s_barrier
	v_mfma_f32_16x16x32_bf16 v[60:63], v[128:131], v[160:163], v[60:63]
	v_mfma_f32_16x16x32_bf16 v[56:59], v[136:139], v[160:163], v[56:59]
	v_mfma_f32_16x16x32_bf16 v[44:47], v[128:131], v[168:171], v[44:47]
	v_mfma_f32_16x16x32_bf16 v[40:43], v[136:139], v[168:171], v[40:43]
	v_mfma_f32_16x16x32_bf16 v[28:31], v[128:131], v[176:179], v[28:31]
	v_mfma_f32_16x16x32_bf16 v[24:27], v[136:139], v[176:179], v[24:27]
	v_mfma_f32_16x16x32_bf16 v[12:15], v[128:131], v[184:187], v[12:15]
	v_mfma_f32_16x16x32_bf16 v[8:11], v[136:139], v[184:187], v[8:11]
	v_mfma_f32_16x16x32_bf16 v[60:63], v[132:135], v[164:167], v[60:63]
	v_mfma_f32_16x16x32_bf16 v[56:59], v[140:143], v[164:167], v[56:59]
	v_mfma_f32_16x16x32_bf16 v[44:47], v[132:135], v[172:175], v[44:47]
	v_mfma_f32_16x16x32_bf16 v[40:43], v[140:143], v[172:175], v[40:43]
	v_mfma_f32_16x16x32_bf16 v[28:31], v[132:135], v[180:183], v[28:31]
	v_mfma_f32_16x16x32_bf16 v[24:27], v[140:143], v[180:183], v[24:27]
	v_mfma_f32_16x16x32_bf16 v[12:15], v[132:135], v[188:191], v[12:15]
	v_mfma_f32_16x16x32_bf16 v[8:11], v[140:143], v[188:191], v[8:11]
	v_mfma_f32_16x16x32_bf16 v[52:55], v[144:147], v[160:163], v[52:55]
	v_mfma_f32_16x16x32_bf16 v[48:51], v[152:155], v[160:163], v[48:51]
	v_mfma_f32_16x16x32_bf16 v[36:39], v[144:147], v[168:171], v[36:39]
	v_mfma_f32_16x16x32_bf16 v[32:35], v[152:155], v[168:171], v[32:35]
	v_mfma_f32_16x16x32_bf16 v[20:23], v[144:147], v[176:179], v[20:23]
	v_mfma_f32_16x16x32_bf16 v[16:19], v[152:155], v[176:179], v[16:19]
	v_mfma_f32_16x16x32_bf16 v[4:7], v[144:147], v[184:187], v[4:7]
	v_mfma_f32_16x16x32_bf16 v[0:3], v[152:155], v[184:187], v[0:3]
	v_mfma_f32_16x16x32_bf16 v[52:55], v[148:151], v[164:167], v[52:55]
	v_mfma_f32_16x16x32_bf16 v[48:51], v[156:159], v[164:167], v[48:51]
	v_mfma_f32_16x16x32_bf16 v[36:39], v[148:151], v[172:175], v[36:39]
	v_mfma_f32_16x16x32_bf16 v[32:35], v[156:159], v[172:175], v[32:35]
	v_mfma_f32_16x16x32_bf16 v[20:23], v[148:151], v[180:183], v[20:23]
	v_mfma_f32_16x16x32_bf16 v[16:19], v[156:159], v[180:183], v[16:19]
	v_mfma_f32_16x16x32_bf16 v[4:7], v[148:151], v[188:191], v[4:7]
	v_mfma_f32_16x16x32_bf16 v[0:3], v[156:159], v[188:191], v[0:3]
	s_barrier
	s_setprio 0
	s_add_i32 s83, s83, 2
	s_add_u32 s80, s80, 0x100
	s_addc_u32 s81, s81, 0
	s_cmp_gt_u32 s83, 13
	s_mov_b64 s[42:43], s[44:45]
	s_cbranch_scc0 .LBB0_507
	v_mov_b32_e32 v233, v227
	v_mov_b32_e32 v144, v226
	s_lshl_b32 s8, s22, 8
	s_or_b32 s8, s8, s73
	v_lshlrev_b32_e32 v208, 3, v233
	v_add_u32_e32 v128, s8, v208
	s_lshr_b32 s8, s20, 4
	s_mul_i32 s42, s8, 0x1800
	s_ashr_i32 s43, s42, 31
	s_lshl_b64 s[42:43], s[42:43], 2
	s_add_u32 s42, s69, s42
	v_ashrrev_i32_e32 v129, 31, v128
	v_add_u32_e32 v210, s72, v144
	s_addc_u32 s43, s70, s43
	v_lshlrev_b64 v[212:213], 2, v[128:129]
	v_lshl_add_u32 v216, s20, 8, v210
	v_lshl_add_u64 v[214:215], s[42:43], 0, v[212:213]
	v_ashrrev_i32_e32 v217, 31, v216
	v_add_co_u32_e32 v128, vcc, s65, v214
	v_lshl_add_u64 v[218:219], s[36:37], 0, v[212:213]
	v_lshlrev_b64 v[144:145], 12, v[216:217]
	v_add_u32_e32 v224, 16, v216
	v_lshl_add_u64 v[132:133], v[214:215], 0, s[10:11]
	v_addc_co_u32_e32 v129, vcc, 0, v215, vcc
	v_lshl_add_u64 v[144:145], v[218:219], 0, v[144:145]
	v_ashrrev_i32_e32 v225, 31, v224
	global_load_dwordx4 v[140:143], v[128:129], off nt
	s_nop 0
	global_load_dwordx4 v[128:131], v[132:133], off offset:528 nt
	global_load_dwordx4 v[136:139], v[132:133], off offset:16 nt
	s_nop 0
	global_load_dwordx4 v[132:135], v[132:133], off offset:512 nt
	s_nop 0
	global_load_dwordx4 v[234:237], v[144:145], off offset:16 nt
	global_load_dwordx4 v[238:241], v[144:145], off nt
	global_load_dwordx4 v[242:245], v[144:145], off offset:528 nt
	global_load_dwordx4 v[246:249], v[144:145], off offset:512 nt
	v_lshlrev_b64 v[144:145], 12, v[224:225]
	v_add_u32_e32 v222, 32, v216
	v_lshl_add_u64 v[144:145], v[218:219], 0, v[144:145]
	v_ashrrev_i32_e32 v223, 31, v222
	global_load_dwordx4 v[184:187], v[144:145], off offset:16 nt
	global_load_dwordx4 v[188:191], v[144:145], off nt
	global_load_dwordx4 v[176:179], v[144:145], off offset:528 nt
	global_load_dwordx4 v[180:183], v[144:145], off offset:512 nt
	v_lshlrev_b64 v[144:145], 12, v[222:223]
	v_add_u32_e32 v220, 48, v216
	v_lshl_add_u64 v[144:145], v[218:219], 0, v[144:145]
	v_ashrrev_i32_e32 v221, 31, v220
	global_load_dwordx4 v[168:171], v[144:145], off offset:16 nt
	global_load_dwordx4 v[172:175], v[144:145], off nt
	global_load_dwordx4 v[160:163], v[144:145], off offset:528 nt
	global_load_dwordx4 v[164:167], v[144:145], off offset:512 nt
	v_lshlrev_b64 v[144:145], 12, v[220:221]
	v_lshl_add_u64 v[148:149], v[218:219], 0, v[144:145]
	global_load_dwordx4 v[152:155], v[148:149], off offset:16 nt
	global_load_dwordx4 v[156:159], v[148:149], off nt
	global_load_dwordx4 v[144:147], v[148:149], off offset:528 nt
	s_nop 0
	global_load_dwordx4 v[148:151], v[148:149], off offset:512 nt
	v_and_b32_e32 v211, 64, v232
	v_xor_b32_e32 v209, 16, v232
	v_add_u32_e32 v211, 64, v211
	v_cmp_lt_i32_e32 vcc, v209, v211
	v_xor_b32_e32 v250, 32, v232
	s_lshl_b32 s42, s22, 2
	v_cndmask_b32_e32 v209, v232, v209, vcc
	v_cmp_lt_i32_e32 vcc, v250, v211
	v_lshlrev_b32_e32 v209, 2, v209
	s_ashr_i32 s43, s42, 31
	v_cndmask_b32_e32 v211, v232, v250, vcc
	v_lshlrev_b32_e32 v211, 2, v211
	v_cmp_eq_u32_e32 vcc, 0, v233
	s_waitcnt vmcnt(0)
	v_pk_fma_f32 v[126:127], v[126:127], v[142:143], v[240:241]
	v_pk_fma_f32 v[124:125], v[124:125], v[140:141], v[238:239]
	v_pk_fma_f32 v[120:121], v[120:121], v[136:137], v[234:235]
	v_mul_f32_e32 v233, v125, v125
	v_mul_f32_e32 v234, v127, v127
	v_fmac_f32_e32 v233, v124, v124
	v_fmac_f32_e32 v234, v126, v126
	v_add_f32_e32 v233, v233, v234
	v_mul_f32_e32 v234, v121, v121
	v_pk_fma_f32 v[122:123], v[122:123], v[138:139], v[236:237]
	v_fmac_f32_e32 v234, v120, v120
	v_add_f32_e32 v233, v233, v234
	v_mul_f32_e32 v234, v123, v123
	v_fmac_f32_e32 v234, v122, v122
	v_pk_fma_f32 v[118:119], v[118:119], v[134:135], v[248:249]
	v_pk_fma_f32 v[116:117], v[116:117], v[132:133], v[246:247]
	v_add_f32_e32 v233, v234, v233
	v_mul_f32_e32 v234, v117, v117
	v_mul_f32_e32 v235, v119, v119
	v_pk_fma_f32 v[112:113], v[112:113], v[128:129], v[242:243]
	v_fmac_f32_e32 v234, v116, v116
	v_fmac_f32_e32 v235, v118, v118
	v_add_f32_e32 v234, v234, v235
	v_mul_f32_e32 v235, v113, v113
	v_pk_fma_f32 v[114:115], v[114:115], v[130:131], v[244:245]
	v_fmac_f32_e32 v235, v112, v112
	v_add_f32_e32 v234, v234, v235
	v_mul_f32_e32 v235, v115, v115
	v_fmac_f32_e32 v235, v114, v114
	v_add_f32_e32 v234, v235, v234
	v_add_f32_e32 v233, v233, v234
	ds_bpermute_b32 v234, v209, v233
	s_waitcnt lgkmcnt(0)
	v_add_f32_e32 v233, v233, v234
	ds_bpermute_b32 v234, v211, v233
	s_and_saveexec_b64 s[44:45], vcc
	s_cbranch_execz .LBB0_510
	v_lshlrev_b64 v[236:237], 6, v[216:217]
	v_lshl_add_u64 v[236:237], s[12:13], 0, v[236:237]
	v_lshl_add_u64 v[236:237], s[42:43], 2, v[236:237]
	s_lshl_b32 s8, s71, 2
	v_lshl_add_u64 v[236:237], v[236:237], 0, s[8:9]
	s_waitcnt lgkmcnt(0)
	v_add_f32_e32 v217, v233, v234
	global_store_dword v[236:237], v217, off

.Lg3_last1:
	s_cmp_eq_u32 s4, 0
	s_cbranch_scc1 .Lg3_dma1
	s_add_i32 m0, s42, 0x2000
	s_add_u32 s42, s48, 0x40000
	s_addc_u32 s43, s49, 0
	s_add_i32 s84, s78, s35
	s_mov_b32 m0, s84
	s_add_i32 m0, s84, 0x2000
	s_mov_b32 m0, s23
	s_mov_b32 m0, s56
	s_waitcnt vmcnt(2)
	s_branch .Lg3_join1
.Lg3_last2:
	s_cmp_eq_u32 s4, 0
	s_cbranch_scc1 .Lg3_dma2
	s_mov_b32 m0, s59
	s_waitcnt vmcnt(0)
	s_branch .Lg3_join2
.Lg3_last3:
	s_cmp_eq_u32 s4, 0
	s_cbranch_scc1 .Lg3_dma3
	s_add_i32 m0, s42, 0x2000
	s_add_u32 s42, s48, 0x40080
	s_addc_u32 s43, s49, 0
	s_add_i32 s48, s85, s35
	s_mov_b32 m0, s48
	s_add_i32 m0, s48, 0x2000
	s_mov_b32 m0, s75
	s_mov_b32 m0, s76
	s_branch .Lg3_join3

.LBB0_568:
	ds_read_b128 v[128:131], v167
	ds_read_b128 v[132:135], v167 offset:1024
	ds_read_b128 v[136:139], v167 offset:2048
	ds_read_b128 v[140:143], v167 offset:3072
	ds_read_b128 v[160:163], v168
	ds_read_b128 v[170:173], v168 offset:1024
	ds_read_b128 v[174:177], v168 offset:2048
	ds_read_b128 v[178:181], v168 offset:3072
	s_add_u32 s36, s28, 0x10000
	s_addc_u32 s37, s29, 0
	s_cmp_eq_u32 s76, 12
	s_cselect_b32 s42, s27, s36
	s_cselect_b32 s43, s19, s37
	s_cselect_b32 s40, s73, s74
	s_cselect_b32 s41, s17, s75
	s_add_u32 s38, s42, 0x8000
	s_addc_u32 s39, s43, 0
	s_add_i32 m0, s44, 0xc000
	ds_read_b128 v[182:185], v169
	ds_read_b128 v[186:189], v169 offset:1024
	ds_read_b128 v[190:193], v169 offset:2048
	ds_read_b128 v[194:197], v169 offset:3072
	ds_read_b128 v[198:201], v169 offset:4096
	ds_read_b128 v[202:205], v169 offset:5120
	ds_read_b128 v[206:209], v169 offset:6144
	ds_read_b128 v[210:213], v169 offset:7168
	global_load_lds_dwordx4 v152, s[28:29]
	s_add_i32 m0, s44, 0xe000
	s_nop 0
	global_load_lds_dwordx4 v154, s[28:29]
	s_waitcnt vmcnt(8)
	s_waitcnt lgkmcnt(0)
	s_setprio 1
	s_barrier
	v_mfma_f32_16x16x32_bf16 v[124:127], v[128:131], v[182:185], v[124:127]
	v_mfma_f32_16x16x32_bf16 v[120:123], v[136:139], v[182:185], v[120:123]
	v_mfma_f32_16x16x32_bf16 v[116:119], v[128:131], v[190:193], v[116:119]
	v_mfma_f32_16x16x32_bf16 v[112:115], v[136:139], v[190:193], v[112:115]
	v_mfma_f32_16x16x32_bf16 v[92:95], v[128:131], v[198:201], v[92:95]
	v_mfma_f32_16x16x32_bf16 v[88:91], v[136:139], v[198:201], v[88:91]
	v_mfma_f32_16x16x32_bf16 v[76:79], v[128:131], v[206:209], v[76:79]
	v_mfma_f32_16x16x32_bf16 v[72:75], v[136:139], v[206:209], v[72:75]
	v_mfma_f32_16x16x32_bf16 v[124:127], v[132:135], v[186:189], v[124:127]
	v_mfma_f32_16x16x32_bf16 v[120:123], v[140:143], v[186:189], v[120:123]
	v_mfma_f32_16x16x32_bf16 v[116:119], v[132:135], v[194:197], v[116:119]
	v_mfma_f32_16x16x32_bf16 v[112:115], v[140:143], v[194:197], v[112:115]
	v_mfma_f32_16x16x32_bf16 v[92:95], v[132:135], v[202:205], v[92:95]
	v_mfma_f32_16x16x32_bf16 v[88:91], v[140:143], v[202:205], v[88:91]
	v_mfma_f32_16x16x32_bf16 v[76:79], v[132:135], v[210:213], v[76:79]
	v_mfma_f32_16x16x32_bf16 v[72:75], v[140:143], v[210:213], v[72:75]
	v_mfma_f32_16x16x32_bf16 v[108:111], v[160:163], v[182:185], v[108:111]
	v_mfma_f32_16x16x32_bf16 v[104:107], v[174:177], v[182:185], v[104:107]
	v_mfma_f32_16x16x32_bf16 v[100:103], v[160:163], v[190:193], v[100:103]
	v_mfma_f32_16x16x32_bf16 v[96:99], v[174:177], v[190:193], v[96:99]
	v_mfma_f32_16x16x32_bf16 v[84:87], v[160:163], v[198:201], v[84:87]
	v_mfma_f32_16x16x32_bf16 v[80:83], v[174:177], v[198:201], v[80:83]
	v_mfma_f32_16x16x32_bf16 v[68:71], v[160:163], v[206:209], v[68:71]
	v_mfma_f32_16x16x32_bf16 v[64:67], v[174:177], v[206:209], v[64:67]
	v_mfma_f32_16x16x32_bf16 v[108:111], v[170:173], v[186:189], v[108:111]
	v_mfma_f32_16x16x32_bf16 v[104:107], v[178:181], v[186:189], v[104:107]
	v_mfma_f32_16x16x32_bf16 v[100:103], v[170:173], v[194:197], v[100:103]
	v_mfma_f32_16x16x32_bf16 v[96:99], v[178:181], v[194:197], v[96:99]
	v_mfma_f32_16x16x32_bf16 v[84:87], v[170:173], v[202:205], v[84:87]
	v_mfma_f32_16x16x32_bf16 v[80:83], v[178:181], v[202:205], v[80:83]
	v_mfma_f32_16x16x32_bf16 v[68:71], v[170:173], v[210:213], v[68:71]
	v_mfma_f32_16x16x32_bf16 v[64:67], v[178:181], v[210:213], v[64:67]
	s_barrier
	s_setprio 0
	s_add_i32 s28, s70, s35
	s_mov_b32 m0, s28
	ds_read_b128 v[182:185], v169 offset:16384
	ds_read_b128 v[186:189], v169 offset:17408
	ds_read_b128 v[190:193], v169 offset:18432
	ds_read_b128 v[194:197], v169 offset:19456
	ds_read_b128 v[198:201], v169 offset:20480
	ds_read_b128 v[202:205], v169 offset:21504
	ds_read_b128 v[206:209], v169 offset:22528
	ds_read_b128 v[210:213], v169 offset:23552
	s_cmp_eq_u32 s76, 12
	s_cbranch_scc1 .Lf1_last1
.Lf1_dma1:
	global_load_lds_dwordx4 v148, s[40:41]
	s_add_i32 m0, s28, 0x2000
	s_add_u32 s28, s40, 0x40000
	s_addc_u32 s29, s41, 0
	s_add_i32 s77, s71, s35
	global_load_lds_dwordx4 v144, s[40:41]
	s_mov_b32 m0, s77
	s_nop 0
	global_load_lds_dwordx4 v148, s[28:29]
	s_add_i32 m0, s77, 0x2000
	s_nop 0
	global_load_lds_dwordx4 v144, s[28:29]
	s_mov_b32 m0, s44
	s_nop 0
	global_load_lds_dwordx4 v150, s[42:43]
	s_mov_b32 m0, s45
	s_nop 0
	global_load_lds_dwordx4 v146, s[42:43]
.Lf1_join1:
	s_waitcnt vmcnt(8)
	s_waitcnt lgkmcnt(0)
	s_setprio 1
	s_barrier
	v_mfma_f32_16x16x32_bf16 v[60:63], v[128:131], v[182:185], v[60:63]
	v_mfma_f32_16x16x32_bf16 v[56:59], v[136:139], v[182:185], v[56:59]
	v_mfma_f32_16x16x32_bf16 v[44:47], v[128:131], v[190:193], v[44:47]
	v_mfma_f32_16x16x32_bf16 v[40:43], v[136:139], v[190:193], v[40:43]
	v_mfma_f32_16x16x32_bf16 v[28:31], v[128:131], v[198:201], v[28:31]
	v_mfma_f32_16x16x32_bf16 v[24:27], v[136:139], v[198:201], v[24:27]
	v_mfma_f32_16x16x32_bf16 v[12:15], v[128:131], v[206:209], v[12:15]
	v_mfma_f32_16x16x32_bf16 v[8:11], v[136:139], v[206:209], v[8:11]
	v_mfma_f32_16x16x32_bf16 v[60:63], v[132:135], v[186:189], v[60:63]
	v_mfma_f32_16x16x32_bf16 v[56:59], v[140:143], v[186:189], v[56:59]
	v_mfma_f32_16x16x32_bf16 v[44:47], v[132:135], v[194:197], v[44:47]
	v_mfma_f32_16x16x32_bf16 v[40:43], v[140:143], v[194:197], v[40:43]
	v_mfma_f32_16x16x32_bf16 v[28:31], v[132:135], v[202:205], v[28:31]
	v_mfma_f32_16x16x32_bf16 v[24:27], v[140:143], v[202:205], v[24:27]
	v_mfma_f32_16x16x32_bf16 v[12:15], v[132:135], v[210:213], v[12:15]
	v_mfma_f32_16x16x32_bf16 v[8:11], v[140:143], v[210:213], v[8:11]
	v_mfma_f32_16x16x32_bf16 v[52:55], v[160:163], v[182:185], v[52:55]
	v_mfma_f32_16x16x32_bf16 v[48:51], v[174:177], v[182:185], v[48:51]
	v_mfma_f32_16x16x32_bf16 v[36:39], v[160:163], v[190:193], v[36:39]
	v_mfma_f32_16x16x32_bf16 v[32:35], v[174:177], v[190:193], v[32:35]
	v_mfma_f32_16x16x32_bf16 v[20:23], v[160:163], v[198:201], v[20:23]
	v_mfma_f32_16x16x32_bf16 v[16:19], v[174:177], v[198:201], v[16:19]
	v_mfma_f32_16x16x32_bf16 v[4:7], v[160:163], v[206:209], v[4:7]
	v_mfma_f32_16x16x32_bf16 v[0:3], v[174:177], v[206:209], v[0:3]
	v_mfma_f32_16x16x32_bf16 v[52:55], v[170:173], v[186:189], v[52:55]
	v_mfma_f32_16x16x32_bf16 v[48:51], v[178:181], v[186:189], v[48:51]
	v_mfma_f32_16x16x32_bf16 v[36:39], v[170:173], v[194:197], v[36:39]
	v_mfma_f32_16x16x32_bf16 v[32:35], v[178:181], v[194:197], v[32:35]
	v_mfma_f32_16x16x32_bf16 v[20:23], v[170:173], v[202:205], v[20:23]
	v_mfma_f32_16x16x32_bf16 v[16:19], v[178:181], v[202:205], v[16:19]
	v_mfma_f32_16x16x32_bf16 v[4:7], v[170:173], v[210:213], v[4:7]
	v_mfma_f32_16x16x32_bf16 v[0:3], v[178:181], v[210:213], v[0:3]
	s_barrier
	s_setprio 0
	s_add_i32 s77, 0, 0x18000
	s_add_i32 s78, 0, 0x1c000
	v_add_u32_e32 v140, s77, v166
	v_add_u32_e32 v178, s78, v166
	ds_read_b128 v[128:131], v140
	ds_read_b128 v[132:135], v140 offset:1024
	ds_read_b128 v[136:139], v140 offset:2048
	ds_read_b128 v[140:143], v140 offset:3072
	ds_read_b128 v[160:163], v178
	ds_read_b128 v[170:173], v178 offset:1024
	ds_read_b128 v[174:177], v178 offset:2048
	ds_read_b128 v[178:181], v178 offset:3072
	s_add_u32 s28, s42, 0x2000
	s_addc_u32 s29, s43, 0
	s_mov_b32 m0, s46
	ds_read_b128 v[182:185], v169 offset:32768
	ds_read_b128 v[186:189], v169 offset:33792
	ds_read_b128 v[190:193], v169 offset:34816
	ds_read_b128 v[194:197], v169 offset:35840
	ds_read_b128 v[198:201], v169 offset:36864
	ds_read_b128 v[202:205], v169 offset:37888
	ds_read_b128 v[206:209], v169 offset:38912
	ds_read_b128 v[210:213], v169 offset:39936
	s_cmp_eq_u32 s76, 12
	s_cbranch_scc1 .Lf1_last2
.Lf1_dma2:
	global_load_lds_dwordx4 v150, s[28:29]
	s_mov_b32 m0, s47
	s_nop 0
	global_load_lds_dwordx4 v146, s[28:29]
.Lf1_join2:
	s_waitcnt vmcnt(8)
	s_waitcnt lgkmcnt(0)
	s_setprio 1
	s_barrier
	v_mfma_f32_16x16x32_bf16 v[124:127], v[128:131], v[182:185], v[124:127]
	v_mfma_f32_16x16x32_bf16 v[120:123], v[136:139], v[182:185], v[120:123]
	v_mfma_f32_16x16x32_bf16 v[116:119], v[128:131], v[190:193], v[116:119]
	v_mfma_f32_16x16x32_bf16 v[112:115], v[136:139], v[190:193], v[112:115]
	v_mfma_f32_16x16x32_bf16 v[92:95], v[128:131], v[198:201], v[92:95]
	v_mfma_f32_16x16x32_bf16 v[88:91], v[136:139], v[198:201], v[88:91]
	v_mfma_f32_16x16x32_bf16 v[76:79], v[128:131], v[206:209], v[76:79]
	v_mfma_f32_16x16x32_bf16 v[72:75], v[136:139], v[206:209], v[72:75]
	v_mfma_f32_16x16x32_bf16 v[124:127], v[132:135], v[186:189], v[124:127]
	v_mfma_f32_16x16x32_bf16 v[120:123], v[140:143], v[186:189], v[120:123]
	v_mfma_f32_16x16x32_bf16 v[116:119], v[132:135], v[194:197], v[116:119]
	v_mfma_f32_16x16x32_bf16 v[112:115], v[140:143], v[194:197], v[112:115]
	v_mfma_f32_16x16x32_bf16 v[92:95], v[132:135], v[202:205], v[92:95]
	v_mfma_f32_16x16x32_bf16 v[88:91], v[140:143], v[202:205], v[88:91]
	v_mfma_f32_16x16x32_bf16 v[76:79], v[132:135], v[210:213], v[76:79]
	v_mfma_f32_16x16x32_bf16 v[72:75], v[140:143], v[210:213], v[72:75]
	v_mfma_f32_16x16x32_bf16 v[108:111], v[160:163], v[182:185], v[108:111]
	v_mfma_f32_16x16x32_bf16 v[104:107], v[174:177], v[182:185], v[104:107]
	v_mfma_f32_16x16x32_bf16 v[100:103], v[160:163], v[190:193], v[100:103]
	v_mfma_f32_16x16x32_bf16 v[96:99], v[174:177], v[190:193], v[96:99]
	v_mfma_f32_16x16x32_bf16 v[84:87], v[160:163], v[198:201], v[84:87]
	v_mfma_f32_16x16x32_bf16 v[80:83], v[174:177], v[198:201], v[80:83]
	v_mfma_f32_16x16x32_bf16 v[68:71], v[160:163], v[206:209], v[68:71]
	v_mfma_f32_16x16x32_bf16 v[64:67], v[174:177], v[206:209], v[64:67]
	v_mfma_f32_16x16x32_bf16 v[108:111], v[170:173], v[186:189], v[108:111]
	v_mfma_f32_16x16x32_bf16 v[104:107], v[178:181], v[186:189], v[104:107]
	v_mfma_f32_16x16x32_bf16 v[100:103], v[170:173], v[194:197], v[100:103]
	v_mfma_f32_16x16x32_bf16 v[96:99], v[178:181], v[194:197], v[96:99]
	v_mfma_f32_16x16x32_bf16 v[84:87], v[170:173], v[202:205], v[84:87]
	v_mfma_f32_16x16x32_bf16 v[80:83], v[178:181], v[202:205], v[80:83]
	v_mfma_f32_16x16x32_bf16 v[68:71], v[170:173], v[210:213], v[68:71]
	v_mfma_f32_16x16x32_bf16 v[64:67], v[178:181], v[210:213], v[64:67]
	s_barrier
	s_setprio 0
	s_add_u32 s98, s40, s12
	s_addc_u32 s99, s41, s13
	s_add_i32 s28, s77, s35
	s_mov_b32 m0, s28
	ds_read_b128 v[182:185], v169 offset:49152
	ds_read_b128 v[186:189], v169 offset:50176
	ds_read_b128 v[190:193], v169 offset:51200
	ds_read_b128 v[194:197], v169 offset:52224
	ds_read_b128 v[198:201], v169 offset:53248
	ds_read_b128 v[202:205], v169 offset:54272
	ds_read_b128 v[206:209], v169 offset:55296
	ds_read_b128 v[210:213], v169 offset:56320
	s_cmp_eq_u32 s76, 12
	s_cbranch_scc1 .Lf1_last3
.Lf1_dma3:
	global_load_lds_dwordx4 v148, s[98:99]
	s_add_i32 m0, s28, 0x2000
	s_add_u32 s28, s40, 0x40080
	s_addc_u32 s29, s41, 0
	s_add_i32 s40, s78, s35
	global_load_lds_dwordx4 v144, s[98:99]
	s_mov_b32 m0, s40
	s_nop 0
	global_load_lds_dwordx4 v148, s[28:29]
	s_add_i32 m0, s40, 0x2000
	s_nop 0
	global_load_lds_dwordx4 v144, s[28:29]
	s_mov_b32 m0, s68
	s_nop 0
	global_load_lds_dwordx4 v150, s[38:39]
	s_mov_b32 m0, s69
	s_nop 0
	global_load_lds_dwordx4 v146, s[38:39]
.Lf1_join3:
	s_waitcnt vmcnt(8)
	s_waitcnt lgkmcnt(0)
	s_setprio 1
	s_barrier
	v_mfma_f32_16x16x32_bf16 v[60:63], v[128:131], v[182:185], v[60:63]
	v_mfma_f32_16x16x32_bf16 v[56:59], v[136:139], v[182:185], v[56:59]
	v_mfma_f32_16x16x32_bf16 v[44:47], v[128:131], v[190:193], v[44:47]
	v_mfma_f32_16x16x32_bf16 v[40:43], v[136:139], v[190:193], v[40:43]
	v_mfma_f32_16x16x32_bf16 v[28:31], v[128:131], v[198:201], v[28:31]
	v_mfma_f32_16x16x32_bf16 v[24:27], v[136:139], v[198:201], v[24:27]
	v_mfma_f32_16x16x32_bf16 v[12:15], v[128:131], v[206:209], v[12:15]
	v_mfma_f32_16x16x32_bf16 v[8:11], v[136:139], v[206:209], v[8:11]
	v_mfma_f32_16x16x32_bf16 v[60:63], v[132:135], v[186:189], v[60:63]
	v_mfma_f32_16x16x32_bf16 v[56:59], v[140:143], v[186:189], v[56:59]
	v_mfma_f32_16x16x32_bf16 v[44:47], v[132:135], v[194:197], v[44:47]
	v_mfma_f32_16x16x32_bf16 v[40:43], v[140:143], v[194:197], v[40:43]
	v_mfma_f32_16x16x32_bf16 v[28:31], v[132:135], v[202:205], v[28:31]
	v_mfma_f32_16x16x32_bf16 v[24:27], v[140:143], v[202:205], v[24:27]
	v_mfma_f32_16x16x32_bf16 v[12:15], v[132:135], v[210:213], v[12:15]
	v_mfma_f32_16x16x32_bf16 v[8:11], v[140:143], v[210:213], v[8:11]
	v_mfma_f32_16x16x32_bf16 v[52:55], v[160:163], v[182:185], v[52:55]
	v_mfma_f32_16x16x32_bf16 v[48:51], v[174:177], v[182:185], v[48:51]
	v_mfma_f32_16x16x32_bf16 v[36:39], v[160:163], v[190:193], v[36:39]
	v_mfma_f32_16x16x32_bf16 v[32:35], v[174:177], v[190:193], v[32:35]
	v_mfma_f32_16x16x32_bf16 v[20:23], v[160:163], v[198:201], v[20:23]
	v_mfma_f32_16x16x32_bf16 v[16:19], v[174:177], v[198:201], v[16:19]
	v_mfma_f32_16x16x32_bf16 v[4:7], v[160:163], v[206:209], v[4:7]
	v_mfma_f32_16x16x32_bf16 v[0:3], v[174:177], v[206:209], v[0:3]
	v_mfma_f32_16x16x32_bf16 v[52:55], v[170:173], v[186:189], v[52:55]
	v_mfma_f32_16x16x32_bf16 v[48:51], v[178:181], v[186:189], v[48:51]
	v_mfma_f32_16x16x32_bf16 v[36:39], v[170:173], v[194:197], v[36:39]
	v_mfma_f32_16x16x32_bf16 v[32:35], v[178:181], v[194:197], v[32:35]
	v_mfma_f32_16x16x32_bf16 v[20:23], v[170:173], v[202:205], v[20:23]
	v_mfma_f32_16x16x32_bf16 v[16:19], v[178:181], v[202:205], v[16:19]
	v_mfma_f32_16x16x32_bf16 v[4:7], v[170:173], v[210:213], v[4:7]
	v_mfma_f32_16x16x32_bf16 v[0:3], v[178:181], v[210:213], v[0:3]
	s_barrier
	s_setprio 0
	s_add_i32 s76, s76, 2
	s_add_u32 s74, s74, 0x100
	s_addc_u32 s75, s75, 0
	s_cmp_gt_u32 s76, 13
	s_mov_b64 s[28:29], s[36:37]
	s_cbranch_scc0 .LBB0_568
	s_and_b64 vcc, exec, s[10:11]
	s_cbranch_vccz .LBB0_571

.Lf1_last1:
	s_cmp_lt_u32 s48, 4
	s_cbranch_scc1 .Lf1_dma1
	s_add_i32 m0, s28, 0x2000
	s_add_u32 s28, s40, 0x40000
	s_addc_u32 s29, s41, 0
	s_add_i32 s77, s71, s35
	s_mov_b32 m0, s77
	s_add_i32 m0, s77, 0x2000
	s_mov_b32 m0, s44
	s_mov_b32 m0, s45
	s_waitcnt vmcnt(2)
	s_branch .Lf1_join1
.Lf1_last2:
	s_cmp_lt_u32 s48, 4
	s_cbranch_scc1 .Lf1_dma2
	s_mov_b32 m0, s47
	s_waitcnt vmcnt(0)
	s_branch .Lf1_join2
.Lf1_last3:
	s_cmp_lt_u32 s48, 4
	s_cbranch_scc1 .Lf1_dma3
	s_add_i32 m0, s28, 0x2000
	s_add_u32 s28, s40, 0x40080
	s_addc_u32 s29, s41, 0
	s_add_i32 s40, s78, s35
	s_mov_b32 m0, s40
	s_add_i32 m0, s40, 0x2000
	s_mov_b32 m0, s68
	s_mov_b32 m0, s69
	s_branch .Lf1_join3
